# NSA compressed unit: next tile's K fragments prefetched right after the current tile's S MFMAs in both passes (S chain issues back to back; hipcc read fragments on demand with a wait each)
# speedup vs baseline: 1.0157x; 1.0073x over previous
; DI f32x16 mfma32(bf16x8 a, bf16x8 b, f32x16 c) { return __builtin_amdgcn_mfma_f32_32x32x16_bf16(a, b, c, 0, 0, 0); }
; DI int crow(int i, int h) { return (i & 3) + 8 * (i >> 2) + 4 * h; }
; DI void nsa_cmp_unit(const Params& p, int u, char* smem) {
;     ...
;     float m = -1e30f, l = 0.f;
; #pragma unroll 1
;     for (int T = 0; T < ntile; ++T) {
;       f32x16 s;
; #pragma unroll
;       for (int i = 0; i < 16; ++i) s[i] = 0.f;
; #pragma unroll
;       for (int ks = 0; ks < 4; ++ks) s = mfma32(*(const bf16x8*)(Kc + (32 * T + r) * LSTR + 16 * ks + 8 * h), qf[ks], s);
;       float mx = -1e30f;
; #pragma unroll
;       for (int i = 0; i < 16; ++i) { const bool valid = (32 * T + crow(i, h)) < nc; const float v = valid ? s[i] : -1e30f; s[i] = v; mx = fmaxf(mx, v); }
;       mx = fmaxf(mx, __shfl_xor(mx, 32));
;       const float mn = fmaxf(m, mx); float ps = 0.f;
; #pragma unroll
;       for (int i = 0; i < 16; ++i) ps += s[i] > -5e29f ? __expf(s[i] - mn) : 0.f;
;       l = l * __expf(m - mn) + ps; m = mn;
;     }
.LBB0_433:
	v_cndmask_b32_e64 v0, 0, 1, s[4:5]
	v_cmp_ne_u32_e64 s[6:7], 1, v0
	v_mov_b32_e32 v0, 0
	v_mov_b32_e32 v140, 0xf149f2ca
	s_andn2_b64 vcc, exec, s[4:5]
	s_cbranch_vccnz .LBB0_436
	v_mov_b32_e32 v50, v129
	v_mov_b32_e32 v51, v128
	s_mov_b32 s8, s31
	ds_read_b128 v[234:237], v51
	ds_read_b128 v[238:241], v51 offset:32
	ds_read_b128 v[242:245], v51 offset:64
	ds_read_b128 v[246:249], v51 offset:96
.LBB0_435:
	s_mov_b32 s9, 0xf149f2ca
	v_mov_b32_e32 v56, v140
	s_add_i32 s8, s8, -1
	s_waitcnt lgkmcnt(0)
	v_mfma_f32_32x32x16_bf16 v[34:49], v[234:237], v[102:105], 0
	s_cmp_lg_u32 s8, 0
	v_mfma_f32_32x32x16_bf16 v[34:49], v[238:241], v[98:101], v[34:49]
	v_mfma_f32_32x32x16_bf16 v[34:49], v[242:245], v[106:109], v[34:49]
	v_add_u32_e32 v51, 0x1200, v51
	v_mfma_f32_32x32x16_bf16 v[34:49], v[246:249], v[110:113], v[34:49]
	ds_read_b128 v[234:237], v51
	ds_read_b128 v[238:241], v51 offset:32
	ds_read_b128 v[242:245], v51 offset:64
	ds_read_b128 v[246:249], v51 offset:96
	v_subrev_u32_e32 v52, 27, v50
	v_cmp_lt_i32_e32 vcc, v52, v116
	v_subrev_u32_e32 v52, 26, v50
	v_subrev_u32_e32 v53, 25, v50
	s_nop 7
	v_cndmask_b32_e32 v34, v206, v34, vcc
	v_cmp_lt_i32_e32 vcc, v52, v116
	s_nop 1
	v_cndmask_b32_e32 v35, v206, v35, vcc
	v_cmp_lt_i32_e32 vcc, v53, v116
	v_subrev_u32_e32 v53, 24, v50
	v_max3_f32 v52, v34, s9, v35
	v_cndmask_b32_e32 v36, v206, v36, vcc
	v_cmp_lt_i32_e32 vcc, v53, v116
	v_subrev_u32_e32 v53, 19, v50
	s_nop 0
	v_cndmask_b32_e32 v37, v206, v37, vcc
	v_cmp_lt_i32_e32 vcc, v53, v116
	v_subrev_u32_e32 v53, 18, v50
	v_max3_f32 v52, v52, v36, v37
	v_cndmask_b32_e32 v38, v206, v38, vcc
	v_cmp_lt_i32_e32 vcc, v53, v116
	v_subrev_u32_e32 v53, 17, v50
	s_nop 0
	v_cndmask_b32_e32 v39, v206, v39, vcc
	v_cmp_lt_i32_e32 vcc, v53, v116
	v_add_u32_e32 v53, -16, v50
	v_max3_f32 v52, v52, v38, v39
	v_cndmask_b32_e32 v40, v206, v40, vcc
	v_cmp_lt_i32_e32 vcc, v53, v116
	v_add_u32_e32 v53, -11, v50
	s_nop 0
	v_cndmask_b32_e32 v41, v206, v41, vcc
	v_cmp_lt_i32_e32 vcc, v53, v116
	v_add_u32_e32 v53, -10, v50
	v_max3_f32 v52, v52, v40, v41
	v_cndmask_b32_e32 v42, v206, v42, vcc
	v_cmp_lt_i32_e32 vcc, v53, v116
	v_add_u32_e32 v53, -9, v50
	s_nop 0
	v_cndmask_b32_e32 v43, v206, v43, vcc
	v_cmp_lt_i32_e32 vcc, v53, v116
	v_add_u32_e32 v53, -8, v50
	v_max3_f32 v52, v52, v42, v43
	v_cndmask_b32_e32 v44, v206, v44, vcc
	v_cmp_lt_i32_e32 vcc, v53, v116
	v_add_u32_e32 v53, -3, v50
	s_nop 0
	v_cndmask_b32_e32 v45, v206, v45, vcc
	v_cmp_lt_i32_e32 vcc, v53, v116
	v_add_u32_e32 v53, -2, v50
	v_max3_f32 v52, v52, v44, v45
	v_cndmask_b32_e32 v46, v206, v46, vcc
	v_cmp_lt_i32_e32 vcc, v53, v116
	v_add_u32_e32 v53, -1, v50
	s_nop 0
	v_cndmask_b32_e32 v47, v206, v47, vcc
	v_cmp_lt_i32_e32 vcc, v53, v116
	v_max3_f32 v52, v52, v46, v47
	s_nop 0
	v_cndmask_b32_e32 v48, v206, v48, vcc
	v_cmp_lt_i32_e32 vcc, v50, v116
	v_add_u32_e32 v50, 32, v50
	s_nop 0
	v_cndmask_b32_e32 v49, v206, v49, vcc
	v_max3_f32 v52, v52, v48, v49
	ds_bpermute_b32 v53, v126, v52
	v_cmp_lt_f32_e32 vcc, s60, v34
	s_waitcnt lgkmcnt(0)
	v_max3_f32 v140, v56, v52, v53
	v_sub_f32_e32 v34, v34, v140
	v_mul_f32_e32 v34, 0x3fb8aa3b, v34
	v_exp_f32_e32 v34, v34
	s_nop 0
	v_add_f32_e32 v34, 0, v34
	v_cndmask_b32_e32 v34, 0, v34, vcc
	v_cmp_lt_f32_e32 vcc, s60, v35
	v_sub_f32_e32 v35, v35, v140
	v_mul_f32_e32 v35, 0x3fb8aa3b, v35
	v_exp_f32_e32 v35, v35
	s_nop 0
	v_cndmask_b32_e32 v35, 0, v35, vcc
	v_add_f32_e32 v34, v35, v34
	v_sub_f32_e32 v35, v36, v140
	v_mul_f32_e32 v35, 0x3fb8aa3b, v35
	v_exp_f32_e32 v35, v35
	v_cmp_lt_f32_e32 vcc, s60, v36
	v_mov_b32_e32 v36, v0
	s_nop 0
	v_cndmask_b32_e32 v35, 0, v35, vcc
	v_add_f32_e32 v34, v35, v34
	v_sub_f32_e32 v35, v37, v140
	v_mul_f32_e32 v35, 0x3fb8aa3b, v35
	v_exp_f32_e32 v35, v35
	v_cmp_lt_f32_e32 vcc, s60, v37
	s_nop 1
	v_cndmask_b32_e32 v35, 0, v35, vcc
	v_add_f32_e32 v34, v35, v34
	v_sub_f32_e32 v35, v38, v140
	v_mul_f32_e32 v35, 0x3fb8aa3b, v35
	v_exp_f32_e32 v35, v35
	v_cmp_lt_f32_e32 vcc, s60, v38
	s_nop 1
	v_cndmask_b32_e32 v35, 0, v35, vcc
	v_add_f32_e32 v34, v35, v34
	v_sub_f32_e32 v35, v39, v140
	v_mul_f32_e32 v35, 0x3fb8aa3b, v35
	v_exp_f32_e32 v35, v35
	v_cmp_lt_f32_e32 vcc, s60, v39
	s_nop 1
	v_cndmask_b32_e32 v35, 0, v35, vcc
	v_add_f32_e32 v34, v35, v34
	v_sub_f32_e32 v35, v40, v140
	v_mul_f32_e32 v35, 0x3fb8aa3b, v35
	v_exp_f32_e32 v35, v35
	v_cmp_lt_f32_e32 vcc, s60, v40
	s_nop 1
	v_cndmask_b32_e32 v35, 0, v35, vcc
	v_add_f32_e32 v34, v35, v34
	v_sub_f32_e32 v35, v41, v140
	v_mul_f32_e32 v35, 0x3fb8aa3b, v35
	v_exp_f32_e32 v35, v35
	v_cmp_lt_f32_e32 vcc, s60, v41
	s_nop 1
	v_cndmask_b32_e32 v35, 0, v35, vcc
	v_add_f32_e32 v34, v35, v34
	v_sub_f32_e32 v35, v42, v140
	v_mul_f32_e32 v35, 0x3fb8aa3b, v35
	v_exp_f32_e32 v35, v35
	v_cmp_lt_f32_e32 vcc, s60, v42
	s_nop 1
	v_cndmask_b32_e32 v35, 0, v35, vcc
	v_add_f32_e32 v34, v35, v34
	v_sub_f32_e32 v35, v43, v140
	v_mul_f32_e32 v35, 0x3fb8aa3b, v35
	v_exp_f32_e32 v35, v35
	v_cmp_lt_f32_e32 vcc, s60, v43
	s_nop 1
	v_cndmask_b32_e32 v35, 0, v35, vcc
	v_add_f32_e32 v34, v35, v34
	v_sub_f32_e32 v35, v44, v140
	v_mul_f32_e32 v35, 0x3fb8aa3b, v35
	v_exp_f32_e32 v35, v35
	v_cmp_lt_f32_e32 vcc, s60, v44
	s_nop 1
	v_cndmask_b32_e32 v35, 0, v35, vcc
	v_add_f32_e32 v34, v35, v34
	v_sub_f32_e32 v35, v45, v140
	v_mul_f32_e32 v35, 0x3fb8aa3b, v35
	v_exp_f32_e32 v35, v35
	v_cmp_lt_f32_e32 vcc, s60, v45
	s_nop 1
	v_cndmask_b32_e32 v35, 0, v35, vcc
	v_add_f32_e32 v34, v35, v34
	v_sub_f32_e32 v35, v46, v140
	v_mul_f32_e32 v35, 0x3fb8aa3b, v35
	v_exp_f32_e32 v35, v35
	v_cmp_lt_f32_e32 vcc, s60, v46
	s_nop 1
	v_cndmask_b32_e32 v35, 0, v35, vcc
	v_add_f32_e32 v34, v35, v34
	v_sub_f32_e32 v35, v47, v140
	v_mul_f32_e32 v35, 0x3fb8aa3b, v35
	v_exp_f32_e32 v35, v35
	v_cmp_lt_f32_e32 vcc, s60, v47
	s_nop 1
	v_cndmask_b32_e32 v35, 0, v35, vcc
	v_add_f32_e32 v34, v35, v34
	v_sub_f32_e32 v35, v48, v140
	v_mul_f32_e32 v35, 0x3fb8aa3b, v35
	v_exp_f32_e32 v35, v35
	v_cmp_lt_f32_e32 vcc, s60, v48
	s_nop 1
	v_cndmask_b32_e32 v35, 0, v35, vcc
	v_add_f32_e32 v34, v35, v34
	v_sub_f32_e32 v35, v49, v140
	v_mul_f32_e32 v35, 0x3fb8aa3b, v35
	v_exp_f32_e32 v35, v35
	v_cmp_lt_f32_e32 vcc, s60, v49
	s_nop 1
	v_cndmask_b32_e32 v35, 0, v35, vcc
	v_add_f32_e32 v34, v35, v34
	v_sub_f32_e32 v35, v56, v140
	v_mul_f32_e32 v35, 0x3fb8aa3b, v35
	v_exp_f32_e32 v35, v35
	v_mov_b32_e32 v0, v34
	v_fmac_f32_e32 v0, v36, v35
	s_cbranch_scc1 .LBB0_435
; DI void nsa_cmp_unit(const Params& p, int u, char* smem) {
;     ...
;     l += __shfl_xor(l, 32);
;     const float inv = l > 0.f ? 1.f / l : 0.f;
;     f32x16 o[2]; zero_o(o);
.LBB0_436:
	ds_bpermute_b32 v34, v126, v0
	s_and_b64 vcc, exec, s[6:7]
	s_cbranch_vccnz .LBB0_447
	s_waitcnt lgkmcnt(0)
	v_add_f32_e32 v0, v0, v34
	v_div_scale_f32 v35, s[6:7], v0, v0, 1.0
	v_rcp_f32_e32 v36, v35
	v_mov_b32_e32 v34, 0
	s_mov_b32 s33, 0
	v_mov_b32_e32 v141, v128
	v_fma_f32 v37, -v35, v36, 1.0
	v_fmac_f32_e32 v36, v37, v36
	v_div_scale_f32 v37, vcc, 1.0, v0, 1.0
	v_mul_f32_e32 v38, v37, v36
	v_fma_f32 v39, -v35, v38, v37
	v_fmac_f32_e32 v38, v39, v36
	v_fma_f32 v35, -v35, v38, v37
	v_div_fmas_f32 v35, v35, v36, v38
	v_div_fixup_f32 v35, v35, v0, 1.0
	v_cmp_lt_f32_e32 vcc, 0, v0
	v_mov_b32_e32 v0, v127
	v_mov_b32_e32 v142, v130
	v_cndmask_b32_e32 v122, 0, v35, vcc
	v_mov_b32_e32 v123, v122
	v_mov_b32_e32 v35, v34
	v_mov_b32_e32 v36, v34
	v_mov_b32_e32 v37, v34
	v_mov_b32_e32 v38, v34
	v_mov_b32_e32 v39, v34
	v_mov_b32_e32 v40, v34
	v_mov_b32_e32 v41, v34
	v_mov_b32_e32 v42, v34
	v_mov_b32_e32 v43, v34
	v_mov_b32_e32 v44, v34
	v_mov_b32_e32 v45, v34
	v_mov_b32_e32 v46, v34
	v_mov_b32_e32 v47, v34
	v_mov_b32_e32 v48, v34
	v_mov_b32_e32 v49, v34
	v_mov_b32_e32 v50, v34
	v_mov_b32_e32 v51, v34
	v_mov_b32_e32 v52, v34
	v_mov_b32_e32 v53, v34
	v_mov_b32_e32 v54, v34
	v_mov_b32_e32 v55, v34
	v_mov_b32_e32 v56, v34
	v_mov_b32_e32 v57, v34
	v_mov_b32_e32 v58, v34
	v_mov_b32_e32 v59, v34
	v_mov_b32_e32 v60, v34
	v_mov_b32_e32 v61, v34
	v_mov_b32_e32 v62, v34
	v_mov_b32_e32 v63, v34
	v_mov_b32_e32 v64, v34
	v_mov_b32_e32 v65, v34
	ds_read_b128 v[234:237], v141
	ds_read_b128 v[238:241], v141 offset:32
	ds_read_b128 v[242:245], v141 offset:64
	ds_read_b128 v[246:249], v141 offset:96
	s_branch .LBB0_439

; DI unsigned pack2(float a, float b) { f32x2 v = {a, b}; bf16x2_t r = __builtin_convertvector(v, bf16x2_t); return __builtin_bit_cast(unsigned, r); }
; DI float bflo(unsigned v) { return __uint_as_float(v << 16); }
; DI float bfhi(unsigned v) { return __uint_as_float(v & 0xffff0000u); }
; DI f32x16 mfma32(bf16x8 a, bf16x8 b, f32x16 c) { return __builtin_amdgcn_mfma_f32_32x32x16_bf16(a, b, c, 0, 0, 0); }
; DI int crow(int i, int h) { return (i & 3) + 8 * (i >> 2) + 4 * h; }
; DI void nsa_cmp_unit(const Params& p, int u, char* smem) {
;     ...
;     for (int T = 0; T < ntile; ++T) {
;       f32x16 s;
; #pragma unroll
;       for (int i = 0; i < 16; ++i) s[i] = 0.f;
; #pragma unroll
;       for (int ks = 0; ks < 4; ++ks) s = mfma32(*(const bf16x8*)(Kc + (32 * T + r) * LSTR + 16 * ks + 8 * h), qf[ks], s);
; #pragma unroll
;       for (int i = 0; i < 16; ++i) { const bool valid = (32 * T + crow(i, h)) < nc; s[i] = valid ? __expf(s[i] - m) * inv : 0.f; }
; #pragma unroll
;       for (int st = 0; st < 2; ++st) {
;         u32x4 ph, pl;
; #pragma unroll
;         for (int e = 0; e < 4; ++e) {
;           const float a0 = s[8 * st + 2 * e], a1 = s[8 * st + 2 * e + 1];
;           const unsigned hw = pack2(a0, a1); ph[e] = hw; pl[e] = pack2(a0 - bflo(hw), a1 - bfhi(hw));
;         }
;         const bf16x8 pbh = __builtin_bit_cast(bf16x8, ph), pbl = __builtin_bit_cast(bf16x8, pl);
; #pragma unroll
;         for (int dt = 0; dt < 2; ++dt) {
;           const s16x4 lo = *(const s16x4*)(Vc + (32 * dt + r) * VSTR + 32 * T + 16 * st + 4 * h);
;           const s16x4 hi = *(const s16x4*)(Vc + (32 * dt + r) * VSTR + 32 * T + 16 * st + 8 + 4 * h);
;           o[dt] = mfma32(__builtin_shufflevector(lo, hi, 0, 1, 2, 3, 4, 5, 6, 7), pbh, o[dt]);
;         }
; #pragma unroll
;         for (int jt = 0; jt < 2; ++jt) {
;           if ((jt == 0 && T <= 3) || (jt == 1 && T >= 3)) {
;             const int base = 32 * T + 16 * st + 4 * h - 128 * jt - 4 * r;
;             bf16x8 ov;
; #pragma unroll
;             for (int jj = 0; jj < 8; ++jj) {
;               const int d = base + 8 * (jj >> 2) + (jj & 3);
;               ov[jj] = (short)((d == -1 || d == 3) ? 0x3F00 : ((d >= 0 && d <= 2) ? 0x3F80 : 0));
;             }
;             imp[jt] = mfma32(ov, pbh, imp[jt]);
;             imp[jt] = mfma32(ov, pbl, imp[jt]);
;           }
.LBB0_439:
	v_or_b32_e32 v152, 2, v0
	s_cmp_lt_u32 s33, 4
	s_cselect_b64 s[8:9], -1, 0
	s_waitcnt lgkmcnt(0)
	v_mfma_f32_32x32x16_bf16 v[66:81], v[234:237], v[102:105], 0
	v_add_u32_e32 v143, v132, v0
	v_mov_b32_e32 v117, v0
	v_mfma_f32_32x32x16_bf16 v[66:81], v[238:241], v[98:101], v[66:81]
	v_mfma_f32_32x32x16_bf16 v[66:81], v[242:245], v[106:109], v[66:81]
	v_add_u32_e32 v146, 1, v0
	v_cmp_lt_i32_e32 vcc, v146, v115
	v_or_b32_e32 v147, 3, v0
	v_mfma_f32_32x32x16_bf16 v[66:81], v[246:249], v[110:113], v[66:81]
	ds_read_b128 v[234:237], v141 offset:4608
	ds_read_b128 v[238:241], v141 offset:4640
	ds_read_b128 v[242:245], v141 offset:4672
	ds_read_b128 v[246:249], v141 offset:4704
	v_or_b32_e32 v150, 10, v0
	s_nop 10
	v_sub_f32_e32 v66, v66, v140
	v_sub_f32_e32 v67, v67, v140
	v_mul_f32_e32 v66, 0x3fb8aa3b, v66
	v_mul_f32_e32 v67, 0x3fb8aa3b, v67
	v_sub_f32_e32 v68, v68, v140
	v_sub_f32_e32 v69, v69, v140
	v_exp_f32_e32 v66, v66
	v_exp_f32_e32 v67, v67
	v_mul_f32_e32 v68, 0x3fb8aa3b, v68
	v_mul_f32_e32 v69, 0x3fb8aa3b, v69
	v_exp_f32_e32 v68, v68
	v_exp_f32_e32 v69, v69
	v_sub_f32_e32 v71, v71, v140
	v_sub_f32_e32 v70, v70, v140
	v_sub_f32_e32 v73, v73, v140
	v_mul_f32_e32 v71, 0x3fb8aa3b, v71
	v_pk_mul_f32 v[66:67], v[122:123], v[66:67]
	v_sub_f32_e32 v72, v72, v140
	v_mul_f32_e32 v70, 0x3fb8aa3b, v70
	v_mul_f32_e32 v145, 0x3fb8aa3b, v73
	v_exp_f32_e32 v73, v71
	v_cndmask_b32_e32 v71, 0, v67, vcc
	v_cmp_lt_i32_e32 vcc, v0, v116
	v_mul_f32_e32 v144, 0x3fb8aa3b, v72
	v_exp_f32_e32 v72, v70
	v_pk_mul_f32 v[68:69], v[122:123], v[68:69]
	v_cndmask_b32_e32 v70, 0, v66, vcc
	v_cmp_lt_i32_e32 vcc, v147, v115
	v_cvt_pk_bf16_f32 v66, v70, v71
	v_lshlrev_b32_e32 v146, 16, v66
	v_cndmask_b32_e32 v69, 0, v69, vcc
	v_cmp_lt_i32_e32 vcc, v152, v116
	v_and_b32_e32 v147, 0xffff0000, v66
	v_exp_f32_e32 v144, v144
	v_cndmask_b32_e32 v68, 0, v68, vcc
	v_cvt_pk_bf16_f32 v67, v68, v69
	v_exp_f32_e32 v145, v145
	v_pk_add_f32 v[70:71], v[70:71], v[146:147] neg_lo:[0,1] neg_hi:[0,1]
	v_lshlrev_b32_e32 v146, 16, v67
	v_and_b32_e32 v147, 0xffff0000, v67
	v_pk_add_f32 v[68:69], v[68:69], v[146:147] neg_lo:[0,1] neg_hi:[0,1]
	v_or_b32_e32 v146, 9, v0
	v_cvt_pk_bf16_f32 v70, v70, v71
	v_cvt_pk_bf16_f32 v71, v68, v69
	v_or_b32_e32 v147, 8, v0
	v_pk_mul_f32 v[68:69], v[122:123], v[72:73]
	v_cmp_lt_i32_e32 vcc, v146, v115
	v_pk_mul_f32 v[144:145], v[122:123], v[144:145]
	s_nop 0
	v_cndmask_b32_e32 v73, 0, v69, vcc
	v_cmp_lt_i32_e32 vcc, v147, v116
	v_or_b32_e32 v69, 11, v0
	ds_read2_b64 v[146:149], v142 offset1:2
	v_cndmask_b32_e32 v72, 0, v68, vcc
	v_cmp_lt_i32_e32 vcc, v69, v115
	v_cvt_pk_bf16_f32 v68, v72, v73
	v_lshlrev_b32_e32 v154, 16, v68
	v_cndmask_b32_e32 v157, 0, v145, vcc
	v_cmp_lt_i32_e32 vcc, v150, v116
	v_and_b32_e32 v155, 0xffff0000, v68
	v_pk_add_f32 v[72:73], v[72:73], v[154:155] neg_lo:[0,1] neg_hi:[0,1]
	v_cndmask_b32_e32 v156, 0, v144, vcc
	v_add_u32_e32 v144, 0x4000, v142
	ds_read2_b64 v[150:153], v144 offset0:64 offset1:66
	v_cvt_pk_bf16_f32 v69, v156, v157
	v_cvt_pk_bf16_f32 v72, v72, v73
	s_and_b64 vcc, exec, s[8:9]
	s_waitcnt lgkmcnt(1)
	v_mfma_f32_32x32x16_bf16 v[34:49], v[146:149], v[66:69], v[34:49]
	v_lshlrev_b32_e32 v146, 16, v69
	v_and_b32_e32 v147, 0xffff0000, v69
	v_add_f32_e64 v146, v156, -v146
	v_add_f32_e64 v147, v157, -v147
	v_cvt_pk_bf16_f32 v73, v146, v147
	s_waitcnt lgkmcnt(0)
	v_mfma_f32_32x32x16_bf16 v[50:65], v[150:153], v[66:69], v[50:65]
	s_cbranch_vccz .LBB0_441
	v_cmp_eq_u32_e32 vcc, v131, v0
	v_add_u32_e32 v146, 1, v143
	v_cmp_gt_i32_e64 s[6:7], 3, v146
	v_cndmask_b32_e32 v145, 0, v207, vcc
	v_cmp_lt_i32_e32 vcc, -1, v143
	s_and_b64 s[6:7], vcc, s[6:7]
	v_add_u32_e32 v147, 2, v143
	v_cndmask_b32_e64 v146, 0, v207, s[6:7]
	v_cmp_gt_i32_e64 s[6:7], 3, v147
	s_and_b64 vcc, vcc, s[6:7]
	v_add_u32_e32 v148, 4, v143
	v_cndmask_b32_e32 v147, 0, v207, vcc
	v_cmp_gt_u32_e32 vcc, 8, v148
	v_add_u32_e32 v149, 9, v143
	v_cmp_gt_i32_e64 s[6:7], 3, v149
	v_cndmask_b32_e32 v150, 0, v208, vcc
	v_cmp_eq_u32_e32 vcc, v133, v0
	v_add_u32_e32 v149, 10, v143
	v_add_u32_e32 v152, 12, v143
	v_cndmask_b32_e32 v148, 0, v207, vcc
	v_cmp_lt_i32_e32 vcc, -9, v143
	s_and_b64 s[6:7], vcc, s[6:7]
	v_cndmask_b32_e64 v151, 0, v207, s[6:7]
	v_cmp_gt_i32_e64 s[6:7], 3, v149
	s_and_b64 vcc, vcc, s[6:7]
	v_cndmask_b32_e32 v149, 0, v207, vcc
	v_cmp_gt_u32_e32 vcc, 8, v152
	v_perm_b32 v148, v151, v148, s61
	v_perm_b32 v147, v150, v147, s61
	v_cndmask_b32_e32 v152, 0, v208, vcc
	v_perm_b32 v149, v152, v149, s61
	v_perm_b32 v146, v146, v145, s61
	s_nop 1
	v_mfma_f32_32x32x16_bf16 v[18:33], v[146:149], v[66:69], v[18:33]
	v_mfma_f32_32x32x16_bf16 v[18:33], v[146:149], v[70:73], v[18:33]
